# EpiMerge epilogue regenerated as a rolling 4-group load pipeline with counted vmcnt waits and SGPR-base 32-bit offsets (same arithmetic)
# speedup vs baseline: 1.0130x; 1.0004x over previous
; #define PG8_STAGE(bufoff, gbase, voff) do { _Pragma("unroll") for (int _i = 0; _i < 2; ++_i) \
;         __builtin_amdgcn_global_load_lds((const unsigned*)((const char*)(gbase) + (voff)[_i]), (LAS unsigned*)(lds + (bufoff) + ldsw + _i * 8192), 16, 0, 0); } while (0)
; #define PG8_LDA(dst, b, h) do { _Pragma("unroll") for (int m = 0; m < 4; ++m) _Pragma("unroll") for (int k = 0; k < 2; ++k) dst[m][k] = *(const LAS bf16x8*)(lds + PG8_SA(b, h) + aoff + m * 2048 + k * 1024); } while (0)
; #define PG8_LDB(dst, b, h) do { _Pragma("unroll") for (int n = 0; n < 2; ++n) _Pragma("unroll") for (int k = 0; k < 2; ++k) dst[n][k] = *(const LAS bf16x8*)(lds + PG8_SB(b, h) + boff + n * 2048 + k * 1024); } while (0)
; #define PG8_MMA(ai, bj, At, Bt) do { __builtin_amdgcn_s_setprio(1); _Pragma("unroll") for (int m = 0; m < 4; ++m) _Pragma("unroll") for (int n = 0; n < 2; ++n) _Pragma("unroll") for (int k = 0; k < 2; ++k) \
;         acc[ai][bj][m][n] = __builtin_amdgcn_mfma_f32_16x16x32_bf16(Bt[n][k], At[m][k], acc[ai][bj][m][n], 0, 0, 0); __builtin_amdgcn_s_setprio(0); } while (0)
; #define PG8_WAIT_L(n) asm volatile("s_waitcnt lgkmcnt(" #n ")" ::: "memory")
; #define PG8_BAR __builtin_amdgcn_s_barrier()
; #define PG8_SCHED __builtin_amdgcn_sched_barrier(0)
; template <class Epi, bool DYN = false>
; __device__ __forceinline__ void gemm_phase(LAS unsigned char* lds, const Gemm g, const Epi& E, int wave, unsigned* ctr = nullptr) {
;     ...
;             PG8_LDB(B0, 0, 0); PG8_SCHED; PG8_LDA(At, 0, 0); PG8_STAGE(PG8_SA(1, 1), a1 + hstepA, voffA);
;             PG8_WAIT_L(8); PG8_BAR; PG8_WAIT_L(0); PG8_MMA(0, 0, At, B0); PG8_BAR; PG8_SCHED;
;             PG8_LDB(B1, 0, 1); PG8_STAGE(PG8_SB(0, 0), b2, voffB);
;             PG8_BAR; PG8_WAIT_L(0); PG8_MMA(0, 1, At, B1); PG8_BAR;
;             PG8_LDA(At, 0, 1); PG8_STAGE(PG8_SA(0, 0), a2, voffA);
;             PG8_BAR; PG8_WAIT_L(0); PG8_MMA(1, 0, At, B0); PG8_BAR; PG8_SCHED;
;             PG8_STAGE(PG8_SB(0, 1), b2 + hstepB, voffB);
.LBB0_118:
	s_add_i32 s9, s8, 2
	s_add_u32 s10, s68, s40
	s_addc_u32 s22, s69, s41
	s_add_i32 s23, 0, 0x10000
	v_add_u32_e32 v146, s23, v244
	ds_read_b128 v[134:137], v146
	ds_read_b128 v[138:141], v146 offset:1024
	ds_read_b128 v[142:145], v146 offset:2048
	ds_read_b128 v[146:149], v146 offset:3072
	s_cmp_eq_u32 s90, s8
	s_cselect_b32 s55, s0, s22
	s_cselect_b32 s54, s1, s10
	s_cselect_b32 s47, s4, s7
	s_cselect_b32 s46, s5, s6
	v_lshl_add_u64 v[182:183], s[68:69], 0, v[130:131]
	s_add_i32 m0, s59, 0xc000
	ds_read_b128 v[150:153], v246
	ds_read_b128 v[154:157], v246 offset:1024
	ds_read_b128 v[158:161], v246 offset:2048
	ds_read_b128 v[162:165], v246 offset:3072
	ds_read_b128 v[166:169], v246 offset:4096
	ds_read_b128 v[170:173], v246 offset:5120
	ds_read_b128 v[174:177], v246 offset:6144
	ds_read_b128 v[178:181], v246 offset:7168
	global_load_lds_dwordx4 v[182:183], off
	v_lshl_add_u64 v[182:183], s[68:69], 0, v[132:133]
	s_add_i32 m0, s59, 0xe000
	s_nop 0
	global_load_lds_dwordx4 v[182:183], off
	s_waitcnt lgkmcnt(8)
	s_barrier
	s_waitcnt lgkmcnt(0)
	s_setprio 1
	s_waitcnt lgkmcnt(0)
	v_mfma_f32_16x16x32_bf16 v[126:129], v[134:137], v[150:153], v[126:129]
	v_mfma_f32_16x16x32_bf16 v[122:125], v[142:145], v[150:153], v[122:125]
	v_mfma_f32_16x16x32_bf16 v[118:121], v[134:137], v[158:161], v[118:121]
	v_mfma_f32_16x16x32_bf16 v[114:117], v[142:145], v[158:161], v[114:117]
	v_mfma_f32_16x16x32_bf16 v[110:113], v[134:137], v[166:169], v[110:113]
	v_mfma_f32_16x16x32_bf16 v[106:109], v[142:145], v[166:169], v[106:109]
	v_mfma_f32_16x16x32_bf16 v[102:105], v[134:137], v[174:177], v[102:105]
	v_mfma_f32_16x16x32_bf16 v[98:101], v[142:145], v[174:177], v[98:101]
	v_mfma_f32_16x16x32_bf16 v[126:129], v[138:141], v[154:157], v[126:129]
	v_mfma_f32_16x16x32_bf16 v[122:125], v[146:149], v[154:157], v[122:125]
	v_mfma_f32_16x16x32_bf16 v[118:121], v[138:141], v[162:165], v[118:121]
	v_mfma_f32_16x16x32_bf16 v[114:117], v[146:149], v[162:165], v[114:117]
	v_mfma_f32_16x16x32_bf16 v[110:113], v[138:141], v[170:173], v[110:113]
	v_mfma_f32_16x16x32_bf16 v[106:109], v[146:149], v[170:173], v[106:109]
	v_mfma_f32_16x16x32_bf16 v[102:105], v[138:141], v[178:181], v[102:105]
	v_mfma_f32_16x16x32_bf16 v[98:101], v[146:149], v[178:181], v[98:101]
	s_setprio 0
	s_barrier
	s_add_i32 s8, 0, 0x14000
	s_add_i32 s10, s23, s83
	v_add_u32_e32 v196, s8, v244
	v_lshl_add_u64 v[210:211], s[46:47], 0, v[200:201]
	s_mov_b32 m0, s10
	ds_read_b128 v[182:185], v196
	ds_read_b128 v[186:189], v196 offset:1024
	ds_read_b128 v[190:193], v196 offset:2048
	ds_read_b128 v[196:199], v196 offset:3072
	global_load_lds_dwordx4 v[210:211], off
	v_lshl_add_u64 v[210:211], s[46:47], 0, v[204:205]
	s_add_i32 m0, s10, 0x2000
	s_nop 0
	global_load_lds_dwordx4 v[210:211], off
	s_barrier
	s_waitcnt lgkmcnt(0)
	s_setprio 1
	s_waitcnt lgkmcnt(0)
	v_mfma_f32_16x16x32_bf16 v[94:97], v[182:185], v[150:153], v[94:97]
	v_mfma_f32_16x16x32_bf16 v[90:93], v[190:193], v[150:153], v[90:93]
	v_mfma_f32_16x16x32_bf16 v[86:89], v[182:185], v[158:161], v[86:89]
	v_mfma_f32_16x16x32_bf16 v[82:85], v[190:193], v[158:161], v[82:85]
	v_mfma_f32_16x16x32_bf16 v[78:81], v[182:185], v[166:169], v[78:81]
	v_mfma_f32_16x16x32_bf16 v[74:77], v[190:193], v[166:169], v[74:77]
	v_mfma_f32_16x16x32_bf16 v[70:73], v[182:185], v[174:177], v[70:73]
	v_mfma_f32_16x16x32_bf16 v[66:69], v[190:193], v[174:177], v[66:69]
	v_mfma_f32_16x16x32_bf16 v[94:97], v[186:189], v[154:157], v[94:97]
	v_mfma_f32_16x16x32_bf16 v[90:93], v[196:199], v[154:157], v[90:93]
	v_mfma_f32_16x16x32_bf16 v[86:89], v[186:189], v[162:165], v[86:89]
	v_mfma_f32_16x16x32_bf16 v[82:85], v[196:199], v[162:165], v[82:85]
	v_mfma_f32_16x16x32_bf16 v[78:81], v[186:189], v[170:173], v[78:81]
	v_mfma_f32_16x16x32_bf16 v[74:77], v[196:199], v[170:173], v[74:77]
	v_mfma_f32_16x16x32_bf16 v[70:73], v[186:189], v[178:181], v[70:73]
	v_mfma_f32_16x16x32_bf16 v[66:69], v[196:199], v[178:181], v[66:69]
	s_setprio 0
	s_mov_b32 m0, s59
	v_lshl_add_u64 v[210:211], s[54:55], 0, v[0:1]
	s_barrier
	ds_read_b128 v[150:153], v246 offset:16384
	ds_read_b128 v[154:157], v246 offset:17408
	ds_read_b128 v[158:161], v246 offset:18432
	ds_read_b128 v[162:165], v246 offset:19456
	ds_read_b128 v[166:169], v246 offset:20480
	ds_read_b128 v[170:173], v246 offset:21504
	ds_read_b128 v[174:177], v246 offset:22528
	ds_read_b128 v[178:181], v246 offset:23552
	global_load_lds_dwordx4 v[210:211], off
	v_lshl_add_u64 v[212:213], s[54:55], 0, v[202:203]
	s_mov_b32 m0, s61
	s_nop 0
	global_load_lds_dwordx4 v[212:213], off
	s_barrier
	s_waitcnt lgkmcnt(0)
	s_setprio 1
	s_waitcnt lgkmcnt(0)
	v_mfma_f32_16x16x32_bf16 v[62:65], v[134:137], v[150:153], v[62:65]
	v_mfma_f32_16x16x32_bf16 v[58:61], v[142:145], v[150:153], v[58:61]
	v_mfma_f32_16x16x32_bf16 v[54:57], v[134:137], v[158:161], v[54:57]
	v_mfma_f32_16x16x32_bf16 v[50:53], v[142:145], v[158:161], v[50:53]
	v_mfma_f32_16x16x32_bf16 v[46:49], v[134:137], v[166:169], v[46:49]
	v_mfma_f32_16x16x32_bf16 v[42:45], v[142:145], v[166:169], v[42:45]
	v_mfma_f32_16x16x32_bf16 v[38:41], v[134:137], v[174:177], v[38:41]
	v_mfma_f32_16x16x32_bf16 v[34:37], v[142:145], v[174:177], v[34:37]
	v_mfma_f32_16x16x32_bf16 v[62:65], v[138:141], v[154:157], v[62:65]
	v_mfma_f32_16x16x32_bf16 v[58:61], v[146:149], v[154:157], v[58:61]
	v_mfma_f32_16x16x32_bf16 v[54:57], v[138:141], v[162:165], v[54:57]
	v_mfma_f32_16x16x32_bf16 v[50:53], v[146:149], v[162:165], v[50:53]
	v_mfma_f32_16x16x32_bf16 v[46:49], v[138:141], v[170:173], v[46:49]
	v_mfma_f32_16x16x32_bf16 v[42:45], v[146:149], v[170:173], v[42:45]
	v_mfma_f32_16x16x32_bf16 v[38:41], v[138:141], v[178:181], v[38:41]
	v_mfma_f32_16x16x32_bf16 v[34:37], v[146:149], v[178:181], v[34:37]
	s_setprio 0
	s_barrier
; #define PG8_STAGE(bufoff, gbase, voff) do { _Pragma("unroll") for (int _i = 0; _i < 2; ++_i) \
;         __builtin_amdgcn_global_load_lds((const unsigned*)((const char*)(gbase) + (voff)[_i]), (LAS unsigned*)(lds + (bufoff) + ldsw + _i * 8192), 16, 0, 0); } while (0)
; #define PG8_LDA(dst, b, h) do { _Pragma("unroll") for (int m = 0; m < 4; ++m) _Pragma("unroll") for (int k = 0; k < 2; ++k) dst[m][k] = *(const LAS bf16x8*)(lds + PG8_SA(b, h) + aoff + m * 2048 + k * 1024); } while (0)
; #define PG8_LDB(dst, b, h) do { _Pragma("unroll") for (int n = 0; n < 2; ++n) _Pragma("unroll") for (int k = 0; k < 2; ++k) dst[n][k] = *(const LAS bf16x8*)(lds + PG8_SB(b, h) + boff + n * 2048 + k * 1024); } while (0)
; #define PG8_MMA(ai, bj, At, Bt) do { __builtin_amdgcn_s_setprio(1); _Pragma("unroll") for (int m = 0; m < 4; ++m) _Pragma("unroll") for (int n = 0; n < 2; ++n) _Pragma("unroll") for (int k = 0; k < 2; ++k) \
;         acc[ai][bj][m][n] = __builtin_amdgcn_mfma_f32_16x16x32_bf16(Bt[n][k], At[m][k], acc[ai][bj][m][n], 0, 0, 0); __builtin_amdgcn_s_setprio(0); } while (0)
; #define PG8_WAIT_V(n) asm volatile("s_waitcnt vmcnt(" #n ")" ::: "memory")
; #define PG8_WAIT_L(n) asm volatile("s_waitcnt lgkmcnt(" #n ")" ::: "memory")
; #define PG8_BAR __builtin_amdgcn_s_barrier()
; #define PG8_SCHED __builtin_amdgcn_sched_barrier(0)
; template <class Epi, bool DYN = false>
; __device__ __forceinline__ void gemm_phase(LAS unsigned char* lds, const Gemm g, const Epi& E, int wave, unsigned* ctr = nullptr) {
;     ...
;             PG8_STAGE(PG8_SB(0, 1), b2 + hstepB, voffB);
;             PG8_WAIT_V(6); PG8_BAR; PG8_MMA(1, 1, At, B1); PG8_BAR;
;             PG8_LDB(B0, 1, 0); PG8_SCHED; PG8_LDA(At, 1, 0); PG8_STAGE(PG8_SA(0, 1), a2 + hstepA, voffA);
;             PG8_WAIT_L(8); PG8_BAR; PG8_WAIT_L(0); PG8_MMA(0, 0, At, B0); PG8_BAR; PG8_SCHED;
;             PG8_LDB(B1, 1, 1); PG8_STAGE(PG8_SB(1, 0), b3, voffB);
;             PG8_BAR; PG8_WAIT_L(0); PG8_MMA(0, 1, At, B1); PG8_BAR;
;             PG8_LDA(At, 1, 1); PG8_STAGE(PG8_SA(1, 0), a3, voffA);
;             PG8_BAR; PG8_WAIT_L(0); PG8_MMA(1, 0, At, B0); PG8_BAR; PG8_SCHED;
	s_add_u32 s22, s46, 0x4000
	s_addc_u32 s23, s47, 0
	s_add_i32 s8, s8, s83
	v_lshl_add_u64 v[134:135], s[22:23], 0, v[200:201]
	s_mov_b32 m0, s8
	s_nop 0
	global_load_lds_dwordx4 v[134:135], off
	v_lshl_add_u64 v[134:135], s[22:23], 0, v[204:205]
	s_add_i32 m0, s8, 0x2000
	s_nop 0
	global_load_lds_dwordx4 v[134:135], off
	s_waitcnt vmcnt(6)
	s_barrier
	s_setprio 1
	v_mfma_f32_16x16x32_bf16 v[30:33], v[182:185], v[150:153], v[30:33]
	v_mfma_f32_16x16x32_bf16 v[26:29], v[190:193], v[150:153], v[26:29]
	v_mfma_f32_16x16x32_bf16 v[22:25], v[182:185], v[158:161], v[22:25]
	v_mfma_f32_16x16x32_bf16 v[18:21], v[190:193], v[158:161], v[18:21]
	v_mfma_f32_16x16x32_bf16 v[14:17], v[182:185], v[166:169], v[14:17]
	v_mfma_f32_16x16x32_bf16 v[10:13], v[190:193], v[166:169], v[10:13]
	v_mfma_f32_16x16x32_bf16 v[6:9], v[182:185], v[174:177], v[6:9]
	v_mfma_f32_16x16x32_bf16 v[2:5], v[190:193], v[174:177], v[2:5]
	v_mfma_f32_16x16x32_bf16 v[30:33], v[186:189], v[154:157], v[30:33]
	v_mfma_f32_16x16x32_bf16 v[26:29], v[196:199], v[154:157], v[26:29]
	v_mfma_f32_16x16x32_bf16 v[22:25], v[186:189], v[162:165], v[22:25]
	v_mfma_f32_16x16x32_bf16 v[18:21], v[196:199], v[162:165], v[18:21]
	v_mfma_f32_16x16x32_bf16 v[14:17], v[186:189], v[170:173], v[14:17]
	v_mfma_f32_16x16x32_bf16 v[10:13], v[196:199], v[170:173], v[10:13]
	v_mfma_f32_16x16x32_bf16 v[6:9], v[186:189], v[178:181], v[6:9]
	v_mfma_f32_16x16x32_bf16 v[2:5], v[196:199], v[178:181], v[2:5]
	s_setprio 0
	s_add_i32 s8, 0, 0x18000
	v_add_u32_e32 v146, s8, v244
	s_barrier
	ds_read_b128 v[134:137], v146
	ds_read_b128 v[138:141], v146 offset:1024
	ds_read_b128 v[142:145], v146 offset:2048
	ds_read_b128 v[146:149], v146 offset:3072
	s_add_u32 s22, s54, s82
	s_addc_u32 s23, s55, 0
	s_mov_b32 m0, s84
	v_lshl_add_u64 v[182:183], s[22:23], 0, v[0:1]
	ds_read_b128 v[150:153], v246 offset:32768
	ds_read_b128 v[154:157], v246 offset:33792
	ds_read_b128 v[158:161], v246 offset:34816
	ds_read_b128 v[162:165], v246 offset:35840
	ds_read_b128 v[166:169], v246 offset:36864
	ds_read_b128 v[170:173], v246 offset:37888
	ds_read_b128 v[174:177], v246 offset:38912
	ds_read_b128 v[178:181], v246 offset:39936
	global_load_lds_dwordx4 v[182:183], off
	v_lshl_add_u64 v[182:183], s[22:23], 0, v[202:203]
	s_mov_b32 m0, s85
	s_nop 0
	global_load_lds_dwordx4 v[182:183], off
	s_waitcnt lgkmcnt(8)
	s_barrier
	s_waitcnt lgkmcnt(0)
	s_setprio 1
	s_waitcnt lgkmcnt(0)
	v_mfma_f32_16x16x32_bf16 v[126:129], v[134:137], v[150:153], v[126:129]
	v_mfma_f32_16x16x32_bf16 v[122:125], v[142:145], v[150:153], v[122:125]
	v_mfma_f32_16x16x32_bf16 v[118:121], v[134:137], v[158:161], v[118:121]
	v_mfma_f32_16x16x32_bf16 v[114:117], v[142:145], v[158:161], v[114:117]
	v_mfma_f32_16x16x32_bf16 v[110:113], v[134:137], v[166:169], v[110:113]
	v_mfma_f32_16x16x32_bf16 v[106:109], v[142:145], v[166:169], v[106:109]
	v_mfma_f32_16x16x32_bf16 v[102:105], v[134:137], v[174:177], v[102:105]
	v_mfma_f32_16x16x32_bf16 v[98:101], v[142:145], v[174:177], v[98:101]
	v_mfma_f32_16x16x32_bf16 v[126:129], v[138:141], v[154:157], v[126:129]
	v_mfma_f32_16x16x32_bf16 v[122:125], v[146:149], v[154:157], v[122:125]
	v_mfma_f32_16x16x32_bf16 v[118:121], v[138:141], v[162:165], v[118:121]
	v_mfma_f32_16x16x32_bf16 v[114:117], v[146:149], v[162:165], v[114:117]
	v_mfma_f32_16x16x32_bf16 v[110:113], v[138:141], v[170:173], v[110:113]
	v_mfma_f32_16x16x32_bf16 v[106:109], v[146:149], v[170:173], v[106:109]
	v_mfma_f32_16x16x32_bf16 v[102:105], v[138:141], v[178:181], v[102:105]
	v_mfma_f32_16x16x32_bf16 v[98:101], v[146:149], v[178:181], v[98:101]
	s_setprio 0
	s_barrier
	s_add_i32 s10, 0, 0x1c000
	s_add_u32 s22, s46, 0x8000
	s_addc_u32 s23, s47, 0
	s_add_i32 s8, s8, s83
	v_add_u32_e32 v196, s10, v244
	v_lshl_add_u64 v[214:215], s[22:23], 0, v[200:201]
	s_mov_b32 m0, s8
	ds_read_b128 v[182:185], v196
	ds_read_b128 v[186:189], v196 offset:1024
	ds_read_b128 v[190:193], v196 offset:2048
	ds_read_b128 v[196:199], v196 offset:3072
	global_load_lds_dwordx4 v[214:215], off
	v_lshl_add_u64 v[214:215], s[22:23], 0, v[204:205]
	s_add_i32 m0, s8, 0x2000
	s_nop 0
	global_load_lds_dwordx4 v[214:215], off
	s_barrier
	s_waitcnt lgkmcnt(0)
	s_setprio 1
	s_waitcnt lgkmcnt(0)
	v_mfma_f32_16x16x32_bf16 v[94:97], v[182:185], v[150:153], v[94:97]
	v_mfma_f32_16x16x32_bf16 v[90:93], v[190:193], v[150:153], v[90:93]
	v_mfma_f32_16x16x32_bf16 v[86:89], v[182:185], v[158:161], v[86:89]
	v_mfma_f32_16x16x32_bf16 v[82:85], v[190:193], v[158:161], v[82:85]
	v_mfma_f32_16x16x32_bf16 v[78:81], v[182:185], v[166:169], v[78:81]
	v_mfma_f32_16x16x32_bf16 v[74:77], v[190:193], v[166:169], v[74:77]
	v_mfma_f32_16x16x32_bf16 v[70:73], v[182:185], v[174:177], v[70:73]
	v_mfma_f32_16x16x32_bf16 v[66:69], v[190:193], v[174:177], v[66:69]
	v_mfma_f32_16x16x32_bf16 v[94:97], v[186:189], v[154:157], v[94:97]
	v_mfma_f32_16x16x32_bf16 v[90:93], v[196:199], v[154:157], v[90:93]
	v_mfma_f32_16x16x32_bf16 v[86:89], v[186:189], v[162:165], v[86:89]
	v_mfma_f32_16x16x32_bf16 v[82:85], v[196:199], v[162:165], v[82:85]
	v_mfma_f32_16x16x32_bf16 v[78:81], v[186:189], v[170:173], v[78:81]
	v_mfma_f32_16x16x32_bf16 v[74:77], v[196:199], v[170:173], v[74:77]
	v_mfma_f32_16x16x32_bf16 v[70:73], v[186:189], v[178:181], v[70:73]
	v_mfma_f32_16x16x32_bf16 v[66:69], v[196:199], v[178:181], v[66:69]
	s_setprio 0
	s_mov_b32 m0, s88
	v_lshl_add_u64 v[210:211], v[210:211], 0, s[52:53]
	s_barrier
; #define PG8_STAGE(bufoff, gbase, voff) do { _Pragma("unroll") for (int _i = 0; _i < 2; ++_i) \
;         __builtin_amdgcn_global_load_lds((const unsigned*)((const char*)(gbase) + (voff)[_i]), (LAS unsigned*)(lds + (bufoff) + ldsw + _i * 8192), 16, 0, 0); } while (0)
; #define PG8_MMA(ai, bj, At, Bt) do { __builtin_amdgcn_s_setprio(1); _Pragma("unroll") for (int m = 0; m < 4; ++m) _Pragma("unroll") for (int n = 0; n < 2; ++n) _Pragma("unroll") for (int k = 0; k < 2; ++k) \
;         acc[ai][bj][m][n] = __builtin_amdgcn_mfma_f32_16x16x32_bf16(Bt[n][k], At[m][k], acc[ai][bj][m][n], 0, 0, 0); __builtin_amdgcn_s_setprio(0); } while (0)
; #define PG8_WAIT_V(n) asm volatile("s_waitcnt vmcnt(" #n ")" ::: "memory")
; #define PG8_WAIT_L(n) asm volatile("s_waitcnt lgkmcnt(" #n ")" ::: "memory")
; #define PG8_BAR __builtin_amdgcn_s_barrier()
; #define PG8_SCHED __builtin_amdgcn_sched_barrier(0)
; template <class Epi, bool DYN = false>
; __device__ __forceinline__ void gemm_phase(LAS unsigned char* lds, const Gemm g, const Epi& E, int wave, unsigned* ctr = nullptr) {
;     ...
;             PG8_BAR; PG8_WAIT_L(0); PG8_MMA(1, 0, At, B0); PG8_BAR; PG8_SCHED;
;             if (DYN && t == 0) publish((ui + 1) & 1);
;             PG8_STAGE(PG8_SB(1, 1), b3 + hstepB, voffB);
;             PG8_WAIT_V(6); PG8_BAR; PG8_MMA(1, 1, At, B1); PG8_BAR;
;     __device__ __forceinline__ void operator()(AccRef acc, const Unit& u, int wr, int wc, int fr, int fq, const float (&pre)[8]) const {
;         const int row0 = u.pm * BM + wr * 64 + fr, col0 = u.pn * BM + wc * 32 + 8 * fq;
; #pragma unroll
;         for (int ai = 0; ai < 2; ++ai) {
;             u32x4 gv[4][2], mv[4][2];
; #pragma unroll
;             for (int m = 0; m < 4; ++m)
; #pragma unroll
;                 for (int bj = 0; bj < 2; ++bj) { const size_t off = (size_t)(row0 + ai * HALF + m * 16) * 2048 + col0 + bj * HALF;
;                     gv[m][bj] = gld16(Gt + off); mv[m][bj] = (u32x4){0u, 0u, 0u, 0u}; if (!first) mv[m][bj] = gld16(Mo + off); }
	ds_read_b128 v[150:153], v246 offset:49152
	ds_read_b128 v[154:157], v246 offset:50176
	ds_read_b128 v[158:161], v246 offset:51200
	ds_read_b128 v[162:165], v246 offset:52224
	ds_read_b128 v[166:169], v246 offset:53248
	ds_read_b128 v[170:173], v246 offset:54272
	ds_read_b128 v[174:177], v246 offset:55296
	ds_read_b128 v[178:181], v246 offset:56320
	global_load_lds_dwordx4 v[210:211], off
	v_lshl_add_u64 v[210:211], v[212:213], 0, s[52:53]
	s_mov_b32 m0, s89
	s_nop 0
	global_load_lds_dwordx4 v[210:211], off
	s_barrier
	s_waitcnt lgkmcnt(0)
	s_setprio 1
	s_waitcnt lgkmcnt(0)
	v_mfma_f32_16x16x32_bf16 v[62:65], v[134:137], v[150:153], v[62:65]
	v_mfma_f32_16x16x32_bf16 v[58:61], v[142:145], v[150:153], v[58:61]
	v_mfma_f32_16x16x32_bf16 v[54:57], v[134:137], v[158:161], v[54:57]
	v_mfma_f32_16x16x32_bf16 v[50:53], v[142:145], v[158:161], v[50:53]
	v_mfma_f32_16x16x32_bf16 v[46:49], v[134:137], v[166:169], v[46:49]
	v_mfma_f32_16x16x32_bf16 v[42:45], v[142:145], v[166:169], v[42:45]
	v_mfma_f32_16x16x32_bf16 v[38:41], v[134:137], v[174:177], v[38:41]
	v_mfma_f32_16x16x32_bf16 v[34:37], v[142:145], v[174:177], v[34:37]
	v_mfma_f32_16x16x32_bf16 v[62:65], v[138:141], v[154:157], v[62:65]
	v_mfma_f32_16x16x32_bf16 v[58:61], v[146:149], v[154:157], v[58:61]
	v_mfma_f32_16x16x32_bf16 v[54:57], v[138:141], v[162:165], v[54:57]
	v_mfma_f32_16x16x32_bf16 v[50:53], v[146:149], v[162:165], v[50:53]
	v_mfma_f32_16x16x32_bf16 v[46:49], v[138:141], v[170:173], v[46:49]
	v_mfma_f32_16x16x32_bf16 v[42:45], v[146:149], v[170:173], v[42:45]
	v_mfma_f32_16x16x32_bf16 v[38:41], v[138:141], v[178:181], v[38:41]
	v_mfma_f32_16x16x32_bf16 v[34:37], v[146:149], v[178:181], v[34:37]
	s_setprio 0
	s_barrier
	s_add_u32 s22, s46, 0xc000
	s_addc_u32 s23, s47, 0
	s_add_i32 s8, s10, s83
	v_lshl_add_u64 v[134:135], s[22:23], 0, v[200:201]
	s_mov_b32 m0, s8
	s_nop 0
	global_load_lds_dwordx4 v[134:135], off
	v_lshl_add_u64 v[134:135], s[22:23], 0, v[204:205]
	s_add_i32 m0, s8, 0x2000
	s_nop 0
	global_load_lds_dwordx4 v[134:135], off
	s_waitcnt vmcnt(6)
	s_barrier
	s_setprio 1
	v_mfma_f32_16x16x32_bf16 v[30:33], v[182:185], v[150:153], v[30:33]
	v_mfma_f32_16x16x32_bf16 v[26:29], v[190:193], v[150:153], v[26:29]
	v_mfma_f32_16x16x32_bf16 v[22:25], v[182:185], v[158:161], v[22:25]
	v_mfma_f32_16x16x32_bf16 v[18:21], v[190:193], v[158:161], v[18:21]
	v_mfma_f32_16x16x32_bf16 v[14:17], v[182:185], v[166:169], v[14:17]
	v_mfma_f32_16x16x32_bf16 v[10:13], v[190:193], v[166:169], v[10:13]
	v_mfma_f32_16x16x32_bf16 v[6:9], v[182:185], v[174:177], v[6:9]
	v_mfma_f32_16x16x32_bf16 v[2:5], v[190:193], v[174:177], v[2:5]
	v_mfma_f32_16x16x32_bf16 v[30:33], v[186:189], v[154:157], v[30:33]
	v_mfma_f32_16x16x32_bf16 v[26:29], v[196:199], v[154:157], v[26:29]
	v_mfma_f32_16x16x32_bf16 v[22:25], v[186:189], v[162:165], v[22:25]
	v_mfma_f32_16x16x32_bf16 v[18:21], v[196:199], v[162:165], v[18:21]
	v_mfma_f32_16x16x32_bf16 v[14:17], v[186:189], v[170:173], v[14:17]
	v_mfma_f32_16x16x32_bf16 v[10:13], v[196:199], v[170:173], v[10:13]
	v_mfma_f32_16x16x32_bf16 v[6:9], v[186:189], v[178:181], v[6:9]
	v_mfma_f32_16x16x32_bf16 v[2:5], v[196:199], v[178:181], v[2:5]
	s_setprio 0
	s_add_u32 s6, s6, 0x10000
	s_addc_u32 s7, s7, 0
	s_add_u32 s40, s40, 0x100
	s_addc_u32 s41, s41, 0
	v_lshl_add_u64 v[132:133], v[132:133], 0, s[56:57]
	v_lshl_add_u64 v[130:131], v[130:131], 0, s[56:57]
	s_cmp_ge_u32 s9, s86
	s_mov_b32 s8, s9
	s_barrier
	s_cbranch_scc0 .LBB0_118
	v_lshl_add_u32 v214, s58, 8, v194
	v_lshl_or_b32 v212, s60, 8, v245
	v_lshlrev_b32_e32 v196, 11, v214
	v_add_u32_e32 v196, v196, v212
	v_lshlrev_b32_e32 v196, 1, v196
	v_add_u32_e32 v197, 0x10000, v196
	v_add_u32_e32 v198, 0x20000, v196
	v_add_u32_e32 v199, 0x30000, v196
	s_andn2_b64 vcc, exec, s[64:65]
	s_cbranch_vccnz .Lmrg_first
	global_load_dwordx4 v[130:133], v196, s[70:71]
	global_load_dwordx4 v[134:137], v196, s[70:71] offset:256
	global_load_dwordx4 v[138:141], v196, s[50:51]
	global_load_dwordx4 v[142:145], v196, s[50:51] offset:256
	global_load_dwordx4 v[146:149], v197, s[70:71]
	global_load_dwordx4 v[150:153], v197, s[70:71] offset:256
	global_load_dwordx4 v[154:157], v197, s[50:51]
	global_load_dwordx4 v[158:161], v197, s[50:51] offset:256
	global_load_dwordx4 v[162:165], v198, s[70:71]
	global_load_dwordx4 v[166:169], v198, s[70:71] offset:256
	global_load_dwordx4 v[170:173], v198, s[50:51]
	global_load_dwordx4 v[174:177], v198, s[50:51] offset:256
	global_load_dwordx4 v[178:181], v199, s[70:71]
	global_load_dwordx4 v[182:185], v199, s[70:71] offset:256
	global_load_dwordx4 v[186:189], v199, s[50:51]
	global_load_dwordx4 v[190:193], v199, s[50:51] offset:256
	s_waitcnt vmcnt(12)
; __device__ __forceinline__ u32x4 pack8(f32x4 v0, f32x4 v1) { u32x4 w; w.x = cvt_pk_bf16(v0[0], v0[1]); w.y = cvt_pk_bf16(v0[2], v0[3]); w.z = cvt_pk_bf16(v1[0], v1[1]); w.w = cvt_pk_bf16(v1[2], v1[3]); return w; }
; __device__ __forceinline__ void unpack8(u32x4 w, f32x4& v0, f32x4& v1) { v0 = (f32x4){bflo(w.x), bfhi(w.x), bflo(w.y), bfhi(w.y)}; v1 = (f32x4){bflo(w.z), bfhi(w.z), bflo(w.w), bfhi(w.w)}; }
;     __device__ __forceinline__ void operator()(AccRef acc, const Unit& u, int wr, int wc, int fr, int fq, const float (&pre)[8]) const {
;     ...
;             for (int m = 0; m < 4; ++m)
; #pragma unroll
;                 for (int bj = 0; bj < 2; ++bj) { const size_t off = (size_t)(row0 + ai * HALF + m * 16) * 2048 + col0 + bj * HALF;
;                     gv[m][bj] = gld16(Gt + off); mv[m][bj] = (u32x4){0u, 0u, 0u, 0u}; if (!first) mv[m][bj] = gld16(Mo + off); }
; #pragma unroll
;             for (int m = 0; m < 4; ++m)
; #pragma unroll
;                 for (int bj = 0; bj < 2; ++bj) { const size_t off = (size_t)(row0 + ai * HALF + m * 16) * 2048 + col0 + bj * HALF;
;                     f32x4 g0, g1; unpack8(gv[m][bj], g0, g1);
;                     f32x4 v0 = g0 * acc[ai][bj][m][0], v1 = g1 * acc[ai][bj][m][1];
;                     { f32x4 p0, p1; unpack8(mv[m][bj], p0, p1); v0 += p0; v1 += p1; }
;                     gst16(Mo + off, pack8(v0, v1)); }
	v_lshlrev_b32_e32 v210, 16, v130
	v_and_b32_e32 v211, 0xffff0000, v130
	v_lshlrev_b32_e32 v212, 16, v138
	v_and_b32_e32 v213, 0xffff0000, v138
	v_pk_fma_f32 v[210:211], v[126:127], v[210:211], v[212:213]
	v_cvt_pk_bf16_f32 v232, v210, v211
	v_lshlrev_b32_e32 v214, 16, v131
	v_and_b32_e32 v215, 0xffff0000, v131
	v_lshlrev_b32_e32 v220, 16, v139
	v_and_b32_e32 v221, 0xffff0000, v139
	v_pk_fma_f32 v[214:215], v[128:129], v[214:215], v[220:221]
	v_cvt_pk_bf16_f32 v233, v214, v215
	v_lshlrev_b32_e32 v210, 16, v132
	v_and_b32_e32 v211, 0xffff0000, v132
	v_lshlrev_b32_e32 v212, 16, v140
	v_and_b32_e32 v213, 0xffff0000, v140
	v_pk_fma_f32 v[210:211], v[122:123], v[210:211], v[212:213]
	v_cvt_pk_bf16_f32 v234, v210, v211
	v_lshlrev_b32_e32 v214, 16, v133
	v_and_b32_e32 v215, 0xffff0000, v133
	v_lshlrev_b32_e32 v220, 16, v141
	v_and_b32_e32 v221, 0xffff0000, v141
	v_pk_fma_f32 v[214:215], v[124:125], v[214:215], v[220:221]
	v_cvt_pk_bf16_f32 v235, v214, v215
	global_store_dwordx4 v196, v[232:235], s[50:51]
	v_lshlrev_b32_e32 v210, 16, v134
	v_and_b32_e32 v211, 0xffff0000, v134
	v_lshlrev_b32_e32 v212, 16, v142
	v_and_b32_e32 v213, 0xffff0000, v142
	v_pk_fma_f32 v[210:211], v[94:95], v[210:211], v[212:213]
	v_cvt_pk_bf16_f32 v216, v210, v211
	v_lshlrev_b32_e32 v214, 16, v135
	v_and_b32_e32 v215, 0xffff0000, v135
	v_lshlrev_b32_e32 v220, 16, v143
	v_and_b32_e32 v221, 0xffff0000, v143
	v_pk_fma_f32 v[214:215], v[96:97], v[214:215], v[220:221]
	v_cvt_pk_bf16_f32 v217, v214, v215
	v_lshlrev_b32_e32 v210, 16, v136
	v_and_b32_e32 v211, 0xffff0000, v136
	v_lshlrev_b32_e32 v212, 16, v144
	v_and_b32_e32 v213, 0xffff0000, v144
	v_pk_fma_f32 v[210:211], v[90:91], v[210:211], v[212:213]
	v_cvt_pk_bf16_f32 v218, v210, v211
	v_lshlrev_b32_e32 v214, 16, v137
	v_and_b32_e32 v215, 0xffff0000, v137
	v_lshlrev_b32_e32 v220, 16, v145
	v_and_b32_e32 v221, 0xffff0000, v145
	v_pk_fma_f32 v[214:215], v[92:93], v[214:215], v[220:221]
	v_cvt_pk_bf16_f32 v219, v214, v215
	global_store_dwordx4 v196, v[216:219], s[50:51] offset:256
	v_add_u32_e32 v196, 0x80000, v196
	global_load_dwordx4 v[130:133], v196, s[70:71]
	global_load_dwordx4 v[134:137], v196, s[70:71] offset:256
	global_load_dwordx4 v[138:141], v196, s[50:51]
	global_load_dwordx4 v[142:145], v196, s[50:51] offset:256
	s_waitcnt vmcnt(14)
	v_lshlrev_b32_e32 v210, 16, v146
	v_and_b32_e32 v211, 0xffff0000, v146
	v_lshlrev_b32_e32 v212, 16, v154
	v_and_b32_e32 v213, 0xffff0000, v154
	v_pk_fma_f32 v[210:211], v[118:119], v[210:211], v[212:213]
	v_cvt_pk_bf16_f32 v232, v210, v211
	v_lshlrev_b32_e32 v214, 16, v147
	v_and_b32_e32 v215, 0xffff0000, v147
	v_lshlrev_b32_e32 v220, 16, v155
	v_and_b32_e32 v221, 0xffff0000, v155
	v_pk_fma_f32 v[214:215], v[120:121], v[214:215], v[220:221]
	v_cvt_pk_bf16_f32 v233, v214, v215
	v_lshlrev_b32_e32 v210, 16, v148
	v_and_b32_e32 v211, 0xffff0000, v148
	v_lshlrev_b32_e32 v212, 16, v156
	v_and_b32_e32 v213, 0xffff0000, v156
	v_pk_fma_f32 v[210:211], v[114:115], v[210:211], v[212:213]
	v_cvt_pk_bf16_f32 v234, v210, v211
	v_lshlrev_b32_e32 v214, 16, v149
	v_and_b32_e32 v215, 0xffff0000, v149
	v_lshlrev_b32_e32 v220, 16, v157
	v_and_b32_e32 v221, 0xffff0000, v157
	v_pk_fma_f32 v[214:215], v[116:117], v[214:215], v[220:221]
	v_cvt_pk_bf16_f32 v235, v214, v215
	global_store_dwordx4 v197, v[232:235], s[50:51]
	v_lshlrev_b32_e32 v210, 16, v150
	v_and_b32_e32 v211, 0xffff0000, v150
	v_lshlrev_b32_e32 v212, 16, v158
	v_and_b32_e32 v213, 0xffff0000, v158
	v_pk_fma_f32 v[210:211], v[86:87], v[210:211], v[212:213]
	v_cvt_pk_bf16_f32 v216, v210, v211
	v_lshlrev_b32_e32 v214, 16, v151
	v_and_b32_e32 v215, 0xffff0000, v151
	v_lshlrev_b32_e32 v220, 16, v159
	v_and_b32_e32 v221, 0xffff0000, v159
	v_pk_fma_f32 v[214:215], v[88:89], v[214:215], v[220:221]
	v_cvt_pk_bf16_f32 v217, v214, v215
	v_lshlrev_b32_e32 v210, 16, v152
	v_and_b32_e32 v211, 0xffff0000, v152
	v_lshlrev_b32_e32 v212, 16, v160
	v_and_b32_e32 v213, 0xffff0000, v160
	v_pk_fma_f32 v[210:211], v[82:83], v[210:211], v[212:213]
	v_cvt_pk_bf16_f32 v218, v210, v211
	v_lshlrev_b32_e32 v214, 16, v153
	v_and_b32_e32 v215, 0xffff0000, v153
	v_lshlrev_b32_e32 v220, 16, v161
	v_and_b32_e32 v221, 0xffff0000, v161
	v_pk_fma_f32 v[214:215], v[84:85], v[214:215], v[220:221]
	v_cvt_pk_bf16_f32 v219, v214, v215
	global_store_dwordx4 v197, v[216:219], s[50:51] offset:256
	v_add_u32_e32 v197, 0x80000, v197
	global_load_dwordx4 v[146:149], v197, s[70:71]
	global_load_dwordx4 v[150:153], v197, s[70:71] offset:256
	global_load_dwordx4 v[154:157], v197, s[50:51]
	global_load_dwordx4 v[158:161], v197, s[50:51] offset:256
	s_waitcnt vmcnt(16)
; __device__ __forceinline__ u32x4 pack8(f32x4 v0, f32x4 v1) { u32x4 w; w.x = cvt_pk_bf16(v0[0], v0[1]); w.y = cvt_pk_bf16(v0[2], v0[3]); w.z = cvt_pk_bf16(v1[0], v1[1]); w.w = cvt_pk_bf16(v1[2], v1[3]); return w; }
; __device__ __forceinline__ void unpack8(u32x4 w, f32x4& v0, f32x4& v1) { v0 = (f32x4){bflo(w.x), bfhi(w.x), bflo(w.y), bfhi(w.y)}; v1 = (f32x4){bflo(w.z), bfhi(w.z), bflo(w.w), bfhi(w.w)}; }
;     __device__ __forceinline__ void operator()(AccRef acc, const Unit& u, int wr, int wc, int fr, int fq, const float (&pre)[8]) const {
;     ...
;         for (int ai = 0; ai < 2; ++ai) {
;             u32x4 gv[4][2], mv[4][2];
; #pragma unroll
;             for (int m = 0; m < 4; ++m)
; #pragma unroll
;                 for (int bj = 0; bj < 2; ++bj) { const size_t off = (size_t)(row0 + ai * HALF + m * 16) * 2048 + col0 + bj * HALF;
;                     gv[m][bj] = gld16(Gt + off); mv[m][bj] = (u32x4){0u, 0u, 0u, 0u}; if (!first) mv[m][bj] = gld16(Mo + off); }
; #pragma unroll
;             for (int m = 0; m < 4; ++m)
; #pragma unroll
;                 for (int bj = 0; bj < 2; ++bj) { const size_t off = (size_t)(row0 + ai * HALF + m * 16) * 2048 + col0 + bj * HALF;
;                     f32x4 g0, g1; unpack8(gv[m][bj], g0, g1);
;                     f32x4 v0 = g0 * acc[ai][bj][m][0], v1 = g1 * acc[ai][bj][m][1];
;                     { f32x4 p0, p1; unpack8(mv[m][bj], p0, p1); v0 += p0; v1 += p1; }
;                     gst16(Mo + off, pack8(v0, v1)); }
	v_lshlrev_b32_e32 v210, 16, v162
	v_and_b32_e32 v211, 0xffff0000, v162
	v_lshlrev_b32_e32 v212, 16, v170
	v_and_b32_e32 v213, 0xffff0000, v170
	v_pk_fma_f32 v[210:211], v[110:111], v[210:211], v[212:213]
	v_cvt_pk_bf16_f32 v232, v210, v211
	v_lshlrev_b32_e32 v214, 16, v163
	v_and_b32_e32 v215, 0xffff0000, v163
	v_lshlrev_b32_e32 v220, 16, v171
	v_and_b32_e32 v221, 0xffff0000, v171
	v_pk_fma_f32 v[214:215], v[112:113], v[214:215], v[220:221]
	v_cvt_pk_bf16_f32 v233, v214, v215
	v_lshlrev_b32_e32 v210, 16, v164
	v_and_b32_e32 v211, 0xffff0000, v164
	v_lshlrev_b32_e32 v212, 16, v172
	v_and_b32_e32 v213, 0xffff0000, v172
	v_pk_fma_f32 v[210:211], v[106:107], v[210:211], v[212:213]
	v_cvt_pk_bf16_f32 v234, v210, v211
	v_lshlrev_b32_e32 v214, 16, v165
	v_and_b32_e32 v215, 0xffff0000, v165
	v_lshlrev_b32_e32 v220, 16, v173
	v_and_b32_e32 v221, 0xffff0000, v173
	v_pk_fma_f32 v[214:215], v[108:109], v[214:215], v[220:221]
	v_cvt_pk_bf16_f32 v235, v214, v215
	global_store_dwordx4 v198, v[232:235], s[50:51]
	v_lshlrev_b32_e32 v210, 16, v166
	v_and_b32_e32 v211, 0xffff0000, v166
	v_lshlrev_b32_e32 v212, 16, v174
	v_and_b32_e32 v213, 0xffff0000, v174
	v_pk_fma_f32 v[210:211], v[78:79], v[210:211], v[212:213]
	v_cvt_pk_bf16_f32 v216, v210, v211
	v_lshlrev_b32_e32 v214, 16, v167
	v_and_b32_e32 v215, 0xffff0000, v167
	v_lshlrev_b32_e32 v220, 16, v175
	v_and_b32_e32 v221, 0xffff0000, v175
	v_pk_fma_f32 v[214:215], v[80:81], v[214:215], v[220:221]
	v_cvt_pk_bf16_f32 v217, v214, v215
	v_lshlrev_b32_e32 v210, 16, v168
	v_and_b32_e32 v211, 0xffff0000, v168
	v_lshlrev_b32_e32 v212, 16, v176
	v_and_b32_e32 v213, 0xffff0000, v176
	v_pk_fma_f32 v[210:211], v[74:75], v[210:211], v[212:213]
	v_cvt_pk_bf16_f32 v218, v210, v211
	v_lshlrev_b32_e32 v214, 16, v169
	v_and_b32_e32 v215, 0xffff0000, v169
	v_lshlrev_b32_e32 v220, 16, v177
	v_and_b32_e32 v221, 0xffff0000, v177
	v_pk_fma_f32 v[214:215], v[76:77], v[214:215], v[220:221]
	v_cvt_pk_bf16_f32 v219, v214, v215
	global_store_dwordx4 v198, v[216:219], s[50:51] offset:256
	v_add_u32_e32 v198, 0x80000, v198
	global_load_dwordx4 v[162:165], v198, s[70:71]
	global_load_dwordx4 v[166:169], v198, s[70:71] offset:256
	global_load_dwordx4 v[170:173], v198, s[50:51]
	global_load_dwordx4 v[174:177], v198, s[50:51] offset:256
	s_waitcnt vmcnt(18)
	v_lshlrev_b32_e32 v210, 16, v178
	v_and_b32_e32 v211, 0xffff0000, v178
	v_lshlrev_b32_e32 v212, 16, v186
	v_and_b32_e32 v213, 0xffff0000, v186
	v_pk_fma_f32 v[210:211], v[102:103], v[210:211], v[212:213]
	v_cvt_pk_bf16_f32 v232, v210, v211
	v_lshlrev_b32_e32 v214, 16, v179
	v_and_b32_e32 v215, 0xffff0000, v179
	v_lshlrev_b32_e32 v220, 16, v187
	v_and_b32_e32 v221, 0xffff0000, v187
	v_pk_fma_f32 v[214:215], v[104:105], v[214:215], v[220:221]
	v_cvt_pk_bf16_f32 v233, v214, v215
	v_lshlrev_b32_e32 v210, 16, v180
	v_and_b32_e32 v211, 0xffff0000, v180
	v_lshlrev_b32_e32 v212, 16, v188
	v_and_b32_e32 v213, 0xffff0000, v188
	v_pk_fma_f32 v[210:211], v[98:99], v[210:211], v[212:213]
	v_cvt_pk_bf16_f32 v234, v210, v211
	v_lshlrev_b32_e32 v214, 16, v181
	v_and_b32_e32 v215, 0xffff0000, v181
	v_lshlrev_b32_e32 v220, 16, v189
	v_and_b32_e32 v221, 0xffff0000, v189
	v_pk_fma_f32 v[214:215], v[100:101], v[214:215], v[220:221]
	v_cvt_pk_bf16_f32 v235, v214, v215
	global_store_dwordx4 v199, v[232:235], s[50:51]
	v_lshlrev_b32_e32 v210, 16, v182
	v_and_b32_e32 v211, 0xffff0000, v182
	v_lshlrev_b32_e32 v212, 16, v190
	v_and_b32_e32 v213, 0xffff0000, v190
	v_pk_fma_f32 v[210:211], v[70:71], v[210:211], v[212:213]
	v_cvt_pk_bf16_f32 v216, v210, v211
	v_lshlrev_b32_e32 v214, 16, v183
	v_and_b32_e32 v215, 0xffff0000, v183
	v_lshlrev_b32_e32 v220, 16, v191
	v_and_b32_e32 v221, 0xffff0000, v191
	v_pk_fma_f32 v[214:215], v[72:73], v[214:215], v[220:221]
	v_cvt_pk_bf16_f32 v217, v214, v215
	v_lshlrev_b32_e32 v210, 16, v184
	v_and_b32_e32 v211, 0xffff0000, v184
	v_lshlrev_b32_e32 v212, 16, v192
	v_and_b32_e32 v213, 0xffff0000, v192
	v_pk_fma_f32 v[210:211], v[66:67], v[210:211], v[212:213]
	v_cvt_pk_bf16_f32 v218, v210, v211
	v_lshlrev_b32_e32 v214, 16, v185
	v_and_b32_e32 v215, 0xffff0000, v185
	v_lshlrev_b32_e32 v220, 16, v193
	v_and_b32_e32 v221, 0xffff0000, v193
	v_pk_fma_f32 v[214:215], v[68:69], v[214:215], v[220:221]
	v_cvt_pk_bf16_f32 v219, v214, v215
	global_store_dwordx4 v199, v[216:219], s[50:51] offset:256
	v_add_u32_e32 v199, 0x80000, v199
	global_load_dwordx4 v[178:181], v199, s[70:71]
	global_load_dwordx4 v[182:185], v199, s[70:71] offset:256
	global_load_dwordx4 v[186:189], v199, s[50:51]
	global_load_dwordx4 v[190:193], v199, s[50:51] offset:256
	s_waitcnt vmcnt(18)
	v_lshlrev_b32_e32 v210, 16, v130
	v_and_b32_e32 v211, 0xffff0000, v130
	v_lshlrev_b32_e32 v212, 16, v138
	v_and_b32_e32 v213, 0xffff0000, v138
	v_pk_fma_f32 v[210:211], v[62:63], v[210:211], v[212:213]
	v_cvt_pk_bf16_f32 v232, v210, v211
	v_lshlrev_b32_e32 v214, 16, v131
	v_and_b32_e32 v215, 0xffff0000, v131
	v_lshlrev_b32_e32 v220, 16, v139
	v_and_b32_e32 v221, 0xffff0000, v139
	v_pk_fma_f32 v[214:215], v[64:65], v[214:215], v[220:221]
	v_cvt_pk_bf16_f32 v233, v214, v215
	v_lshlrev_b32_e32 v210, 16, v132
	v_and_b32_e32 v211, 0xffff0000, v132
	v_lshlrev_b32_e32 v212, 16, v140
	v_and_b32_e32 v213, 0xffff0000, v140
	v_pk_fma_f32 v[210:211], v[58:59], v[210:211], v[212:213]
	v_cvt_pk_bf16_f32 v234, v210, v211
	v_lshlrev_b32_e32 v214, 16, v133
	v_and_b32_e32 v215, 0xffff0000, v133
	v_lshlrev_b32_e32 v220, 16, v141
	v_and_b32_e32 v221, 0xffff0000, v141
	v_pk_fma_f32 v[214:215], v[60:61], v[214:215], v[220:221]
	v_cvt_pk_bf16_f32 v235, v214, v215
	global_store_dwordx4 v196, v[232:235], s[50:51]
	v_lshlrev_b32_e32 v210, 16, v134
	v_and_b32_e32 v211, 0xffff0000, v134
	v_lshlrev_b32_e32 v212, 16, v142
	v_and_b32_e32 v213, 0xffff0000, v142
	v_pk_fma_f32 v[210:211], v[30:31], v[210:211], v[212:213]
	v_cvt_pk_bf16_f32 v216, v210, v211
	v_lshlrev_b32_e32 v214, 16, v135
	v_and_b32_e32 v215, 0xffff0000, v135
	v_lshlrev_b32_e32 v220, 16, v143
	v_and_b32_e32 v221, 0xffff0000, v143
	v_pk_fma_f32 v[214:215], v[32:33], v[214:215], v[220:221]
	v_cvt_pk_bf16_f32 v217, v214, v215
	v_lshlrev_b32_e32 v210, 16, v136
	v_and_b32_e32 v211, 0xffff0000, v136
	v_lshlrev_b32_e32 v212, 16, v144
	v_and_b32_e32 v213, 0xffff0000, v144
	v_pk_fma_f32 v[210:211], v[26:27], v[210:211], v[212:213]
	v_cvt_pk_bf16_f32 v218, v210, v211
	v_lshlrev_b32_e32 v214, 16, v137
	v_and_b32_e32 v215, 0xffff0000, v137
	v_lshlrev_b32_e32 v220, 16, v145
	v_and_b32_e32 v221, 0xffff0000, v145
	v_pk_fma_f32 v[214:215], v[28:29], v[214:215], v[220:221]
	v_cvt_pk_bf16_f32 v219, v214, v215
	global_store_dwordx4 v196, v[216:219], s[50:51] offset:256
	s_waitcnt vmcnt(14)
; __device__ __forceinline__ u32x4 pack8(f32x4 v0, f32x4 v1) { u32x4 w; w.x = cvt_pk_bf16(v0[0], v0[1]); w.y = cvt_pk_bf16(v0[2], v0[3]); w.z = cvt_pk_bf16(v1[0], v1[1]); w.w = cvt_pk_bf16(v1[2], v1[3]); return w; }
; __device__ __forceinline__ void unpack8(u32x4 w, f32x4& v0, f32x4& v1) { v0 = (f32x4){bflo(w.x), bfhi(w.x), bflo(w.y), bfhi(w.y)}; v1 = (f32x4){bflo(w.z), bfhi(w.z), bflo(w.w), bfhi(w.w)}; }
;     __device__ __forceinline__ void operator()(AccRef acc, const Unit& u, int wr, int wc, int fr, int fq, const float (&pre)[8]) const {
;     ...
;         for (int ai = 0; ai < 2; ++ai) {
;             u32x4 gv[4][2], mv[4][2];
; #pragma unroll
;             for (int m = 0; m < 4; ++m)
; #pragma unroll
;                 for (int bj = 0; bj < 2; ++bj) { const size_t off = (size_t)(row0 + ai * HALF + m * 16) * 2048 + col0 + bj * HALF;
;                     gv[m][bj] = gld16(Gt + off); mv[m][bj] = (u32x4){0u, 0u, 0u, 0u}; if (!first) mv[m][bj] = gld16(Mo + off); }
; #pragma unroll
;             for (int m = 0; m < 4; ++m)
; #pragma unroll
;                 for (int bj = 0; bj < 2; ++bj) { const size_t off = (size_t)(row0 + ai * HALF + m * 16) * 2048 + col0 + bj * HALF;
;                     f32x4 g0, g1; unpack8(gv[m][bj], g0, g1);
;                     f32x4 v0 = g0 * acc[ai][bj][m][0], v1 = g1 * acc[ai][bj][m][1];
;                     { f32x4 p0, p1; unpack8(mv[m][bj], p0, p1); v0 += p0; v1 += p1; }
;                     gst16(Mo + off, pack8(v0, v1)); }
	v_lshlrev_b32_e32 v210, 16, v146
	v_and_b32_e32 v211, 0xffff0000, v146
	v_lshlrev_b32_e32 v212, 16, v154
	v_and_b32_e32 v213, 0xffff0000, v154
	v_pk_fma_f32 v[210:211], v[54:55], v[210:211], v[212:213]
	v_cvt_pk_bf16_f32 v232, v210, v211
	v_lshlrev_b32_e32 v214, 16, v147
	v_and_b32_e32 v215, 0xffff0000, v147
	v_lshlrev_b32_e32 v220, 16, v155
	v_and_b32_e32 v221, 0xffff0000, v155
	v_pk_fma_f32 v[214:215], v[56:57], v[214:215], v[220:221]
	v_cvt_pk_bf16_f32 v233, v214, v215
	v_lshlrev_b32_e32 v210, 16, v148
	v_and_b32_e32 v211, 0xffff0000, v148
	v_lshlrev_b32_e32 v212, 16, v156
	v_and_b32_e32 v213, 0xffff0000, v156
	v_pk_fma_f32 v[210:211], v[50:51], v[210:211], v[212:213]
	v_cvt_pk_bf16_f32 v234, v210, v211
	v_lshlrev_b32_e32 v214, 16, v149
	v_and_b32_e32 v215, 0xffff0000, v149
	v_lshlrev_b32_e32 v220, 16, v157
	v_and_b32_e32 v221, 0xffff0000, v157
	v_pk_fma_f32 v[214:215], v[52:53], v[214:215], v[220:221]
	v_cvt_pk_bf16_f32 v235, v214, v215
	global_store_dwordx4 v197, v[232:235], s[50:51]
	v_lshlrev_b32_e32 v210, 16, v150
	v_and_b32_e32 v211, 0xffff0000, v150
	v_lshlrev_b32_e32 v212, 16, v158
	v_and_b32_e32 v213, 0xffff0000, v158
	v_pk_fma_f32 v[210:211], v[22:23], v[210:211], v[212:213]
	v_cvt_pk_bf16_f32 v216, v210, v211
	v_lshlrev_b32_e32 v214, 16, v151
	v_and_b32_e32 v215, 0xffff0000, v151
	v_lshlrev_b32_e32 v220, 16, v159
	v_and_b32_e32 v221, 0xffff0000, v159
	v_pk_fma_f32 v[214:215], v[24:25], v[214:215], v[220:221]
	v_cvt_pk_bf16_f32 v217, v214, v215
	v_lshlrev_b32_e32 v210, 16, v152
	v_and_b32_e32 v211, 0xffff0000, v152
	v_lshlrev_b32_e32 v212, 16, v160
	v_and_b32_e32 v213, 0xffff0000, v160
	v_pk_fma_f32 v[210:211], v[18:19], v[210:211], v[212:213]
	v_cvt_pk_bf16_f32 v218, v210, v211
	v_lshlrev_b32_e32 v214, 16, v153
	v_and_b32_e32 v215, 0xffff0000, v153
	v_lshlrev_b32_e32 v220, 16, v161
	v_and_b32_e32 v221, 0xffff0000, v161
	v_pk_fma_f32 v[214:215], v[20:21], v[214:215], v[220:221]
	v_cvt_pk_bf16_f32 v219, v214, v215
	global_store_dwordx4 v197, v[216:219], s[50:51] offset:256
	s_waitcnt vmcnt(10)
	v_lshlrev_b32_e32 v210, 16, v162
	v_and_b32_e32 v211, 0xffff0000, v162
	v_lshlrev_b32_e32 v212, 16, v170
	v_and_b32_e32 v213, 0xffff0000, v170
	v_pk_fma_f32 v[210:211], v[46:47], v[210:211], v[212:213]
	v_cvt_pk_bf16_f32 v232, v210, v211
	v_lshlrev_b32_e32 v214, 16, v163
	v_and_b32_e32 v215, 0xffff0000, v163
	v_lshlrev_b32_e32 v220, 16, v171
	v_and_b32_e32 v221, 0xffff0000, v171
	v_pk_fma_f32 v[214:215], v[48:49], v[214:215], v[220:221]
	v_cvt_pk_bf16_f32 v233, v214, v215
	v_lshlrev_b32_e32 v210, 16, v164
	v_and_b32_e32 v211, 0xffff0000, v164
	v_lshlrev_b32_e32 v212, 16, v172
	v_and_b32_e32 v213, 0xffff0000, v172
	v_pk_fma_f32 v[210:211], v[42:43], v[210:211], v[212:213]
	v_cvt_pk_bf16_f32 v234, v210, v211
	v_lshlrev_b32_e32 v214, 16, v165
	v_and_b32_e32 v215, 0xffff0000, v165
	v_lshlrev_b32_e32 v220, 16, v173
	v_and_b32_e32 v221, 0xffff0000, v173
	v_pk_fma_f32 v[214:215], v[44:45], v[214:215], v[220:221]
	v_cvt_pk_bf16_f32 v235, v214, v215
	global_store_dwordx4 v198, v[232:235], s[50:51]
	v_lshlrev_b32_e32 v210, 16, v166
	v_and_b32_e32 v211, 0xffff0000, v166
	v_lshlrev_b32_e32 v212, 16, v174
	v_and_b32_e32 v213, 0xffff0000, v174
	v_pk_fma_f32 v[210:211], v[14:15], v[210:211], v[212:213]
	v_cvt_pk_bf16_f32 v216, v210, v211
	v_lshlrev_b32_e32 v214, 16, v167
	v_and_b32_e32 v215, 0xffff0000, v167
	v_lshlrev_b32_e32 v220, 16, v175
	v_and_b32_e32 v221, 0xffff0000, v175
	v_pk_fma_f32 v[214:215], v[16:17], v[214:215], v[220:221]
	v_cvt_pk_bf16_f32 v217, v214, v215
	v_lshlrev_b32_e32 v210, 16, v168
	v_and_b32_e32 v211, 0xffff0000, v168
	v_lshlrev_b32_e32 v212, 16, v176
	v_and_b32_e32 v213, 0xffff0000, v176
	v_pk_fma_f32 v[210:211], v[10:11], v[210:211], v[212:213]
	v_cvt_pk_bf16_f32 v218, v210, v211
	v_lshlrev_b32_e32 v214, 16, v169
	v_and_b32_e32 v215, 0xffff0000, v169
	v_lshlrev_b32_e32 v220, 16, v177
	v_and_b32_e32 v221, 0xffff0000, v177
	v_pk_fma_f32 v[214:215], v[12:13], v[214:215], v[220:221]
	v_cvt_pk_bf16_f32 v219, v214, v215
	global_store_dwordx4 v198, v[216:219], s[50:51] offset:256
	s_waitcnt vmcnt(6)
	v_lshlrev_b32_e32 v210, 16, v178
	v_and_b32_e32 v211, 0xffff0000, v178
	v_lshlrev_b32_e32 v212, 16, v186
	v_and_b32_e32 v213, 0xffff0000, v186
	v_pk_fma_f32 v[210:211], v[38:39], v[210:211], v[212:213]
	v_cvt_pk_bf16_f32 v232, v210, v211
	v_lshlrev_b32_e32 v214, 16, v179
	v_and_b32_e32 v215, 0xffff0000, v179
	v_lshlrev_b32_e32 v220, 16, v187
	v_and_b32_e32 v221, 0xffff0000, v187
	v_pk_fma_f32 v[214:215], v[40:41], v[214:215], v[220:221]
	v_cvt_pk_bf16_f32 v233, v214, v215
	v_lshlrev_b32_e32 v210, 16, v180
	v_and_b32_e32 v211, 0xffff0000, v180
	v_lshlrev_b32_e32 v212, 16, v188
	v_and_b32_e32 v213, 0xffff0000, v188
	v_pk_fma_f32 v[210:211], v[34:35], v[210:211], v[212:213]
	v_cvt_pk_bf16_f32 v234, v210, v211
	v_lshlrev_b32_e32 v214, 16, v181
	v_and_b32_e32 v215, 0xffff0000, v181
	v_lshlrev_b32_e32 v220, 16, v189
	v_and_b32_e32 v221, 0xffff0000, v189
	v_pk_fma_f32 v[214:215], v[36:37], v[214:215], v[220:221]
	v_cvt_pk_bf16_f32 v235, v214, v215
	global_store_dwordx4 v199, v[232:235], s[50:51]
	v_lshlrev_b32_e32 v210, 16, v182
	v_and_b32_e32 v211, 0xffff0000, v182
	v_lshlrev_b32_e32 v212, 16, v190
	v_and_b32_e32 v213, 0xffff0000, v190
	v_pk_fma_f32 v[210:211], v[6:7], v[210:211], v[212:213]
	v_cvt_pk_bf16_f32 v216, v210, v211
	v_lshlrev_b32_e32 v214, 16, v183
	v_and_b32_e32 v215, 0xffff0000, v183
	v_lshlrev_b32_e32 v220, 16, v191
	v_and_b32_e32 v221, 0xffff0000, v191
	v_pk_fma_f32 v[214:215], v[8:9], v[214:215], v[220:221]
	v_cvt_pk_bf16_f32 v217, v214, v215
	v_lshlrev_b32_e32 v210, 16, v184
	v_and_b32_e32 v211, 0xffff0000, v184
	v_lshlrev_b32_e32 v212, 16, v192
	v_and_b32_e32 v213, 0xffff0000, v192
	v_pk_fma_f32 v[210:211], v[2:3], v[210:211], v[212:213]
	v_cvt_pk_bf16_f32 v218, v210, v211
	v_lshlrev_b32_e32 v214, 16, v185
	v_and_b32_e32 v215, 0xffff0000, v185
	v_lshlrev_b32_e32 v220, 16, v193
	v_and_b32_e32 v221, 0xffff0000, v193
	v_pk_fma_f32 v[214:215], v[4:5], v[214:215], v[220:221]
	v_cvt_pk_bf16_f32 v219, v214, v215
	global_store_dwordx4 v199, v[216:219], s[50:51] offset:256
	s_branch .Lmrg_done
; __device__ __forceinline__ u32x4 pack8(f32x4 v0, f32x4 v1) { u32x4 w; w.x = cvt_pk_bf16(v0[0], v0[1]); w.y = cvt_pk_bf16(v0[2], v0[3]); w.z = cvt_pk_bf16(v1[0], v1[1]); w.w = cvt_pk_bf16(v1[2], v1[3]); return w; }
; __device__ __forceinline__ void unpack8(u32x4 w, f32x4& v0, f32x4& v1) { v0 = (f32x4){bflo(w.x), bfhi(w.x), bflo(w.y), bfhi(w.y)}; v1 = (f32x4){bflo(w.z), bfhi(w.z), bflo(w.w), bfhi(w.w)}; }
;     __device__ __forceinline__ void operator()(AccRef acc, const Unit& u, int wr, int wc, int fr, int fq, const float (&pre)[8]) const {
;     ...
;         for (int ai = 0; ai < 2; ++ai) {
;             u32x4 gv[4][2], mv[4][2];
; #pragma unroll
;             for (int m = 0; m < 4; ++m)
; #pragma unroll
;                 for (int bj = 0; bj < 2; ++bj) { const size_t off = (size_t)(row0 + ai * HALF + m * 16) * 2048 + col0 + bj * HALF;
;                     gv[m][bj] = gld16(Gt + off); mv[m][bj] = (u32x4){0u, 0u, 0u, 0u}; if (!first) mv[m][bj] = gld16(Mo + off); }
; #pragma unroll
;             for (int m = 0; m < 4; ++m)
; #pragma unroll
;                 for (int bj = 0; bj < 2; ++bj) { const size_t off = (size_t)(row0 + ai * HALF + m * 16) * 2048 + col0 + bj * HALF;
;                     f32x4 g0, g1; unpack8(gv[m][bj], g0, g1);
;                     f32x4 v0 = g0 * acc[ai][bj][m][0], v1 = g1 * acc[ai][bj][m][1];
;                     { f32x4 p0, p1; unpack8(mv[m][bj], p0, p1); v0 += p0; v1 += p1; }
;                     gst16(Mo + off, pack8(v0, v1)); }
.Lmrg_first:
	global_load_dwordx4 v[130:133], v196, s[70:71]
	global_load_dwordx4 v[134:137], v196, s[70:71] offset:256
	global_load_dwordx4 v[146:149], v197, s[70:71]
	global_load_dwordx4 v[150:153], v197, s[70:71] offset:256
	global_load_dwordx4 v[162:165], v198, s[70:71]
	global_load_dwordx4 v[166:169], v198, s[70:71] offset:256
	global_load_dwordx4 v[178:181], v199, s[70:71]
	global_load_dwordx4 v[182:185], v199, s[70:71] offset:256
	v_mov_b32_e32 v212, 0
	v_mov_b32_e32 v213, 0
	v_mov_b32_e32 v220, 0
	v_mov_b32_e32 v221, 0
	s_waitcnt vmcnt(6)
	v_lshlrev_b32_e32 v210, 16, v130
	v_and_b32_e32 v211, 0xffff0000, v130
	v_pk_fma_f32 v[210:211], v[126:127], v[210:211], v[212:213]
	v_cvt_pk_bf16_f32 v232, v210, v211
	v_lshlrev_b32_e32 v214, 16, v131
	v_and_b32_e32 v215, 0xffff0000, v131
	v_pk_fma_f32 v[214:215], v[128:129], v[214:215], v[220:221]
	v_cvt_pk_bf16_f32 v233, v214, v215
	v_lshlrev_b32_e32 v210, 16, v132
	v_and_b32_e32 v211, 0xffff0000, v132
	v_pk_fma_f32 v[210:211], v[122:123], v[210:211], v[212:213]
	v_cvt_pk_bf16_f32 v234, v210, v211
	v_lshlrev_b32_e32 v214, 16, v133
	v_and_b32_e32 v215, 0xffff0000, v133
	v_pk_fma_f32 v[214:215], v[124:125], v[214:215], v[220:221]
	v_cvt_pk_bf16_f32 v235, v214, v215
	global_store_dwordx4 v196, v[232:235], s[50:51]
	v_lshlrev_b32_e32 v210, 16, v134
	v_and_b32_e32 v211, 0xffff0000, v134
	v_pk_fma_f32 v[210:211], v[94:95], v[210:211], v[212:213]
	v_cvt_pk_bf16_f32 v216, v210, v211
	v_lshlrev_b32_e32 v214, 16, v135
	v_and_b32_e32 v215, 0xffff0000, v135
	v_pk_fma_f32 v[214:215], v[96:97], v[214:215], v[220:221]
	v_cvt_pk_bf16_f32 v217, v214, v215
	v_lshlrev_b32_e32 v210, 16, v136
	v_and_b32_e32 v211, 0xffff0000, v136
	v_pk_fma_f32 v[210:211], v[90:91], v[210:211], v[212:213]
	v_cvt_pk_bf16_f32 v218, v210, v211
	v_lshlrev_b32_e32 v214, 16, v137
	v_and_b32_e32 v215, 0xffff0000, v137
	v_pk_fma_f32 v[214:215], v[92:93], v[214:215], v[220:221]
	v_cvt_pk_bf16_f32 v219, v214, v215
	global_store_dwordx4 v196, v[216:219], s[50:51] offset:256
	v_add_u32_e32 v196, 0x80000, v196
	global_load_dwordx4 v[130:133], v196, s[70:71]
	global_load_dwordx4 v[134:137], v196, s[70:71] offset:256
	s_waitcnt vmcnt(8)
	v_lshlrev_b32_e32 v210, 16, v146
	v_and_b32_e32 v211, 0xffff0000, v146
	v_pk_fma_f32 v[210:211], v[118:119], v[210:211], v[212:213]
	v_cvt_pk_bf16_f32 v232, v210, v211
	v_lshlrev_b32_e32 v214, 16, v147
	v_and_b32_e32 v215, 0xffff0000, v147
	v_pk_fma_f32 v[214:215], v[120:121], v[214:215], v[220:221]
	v_cvt_pk_bf16_f32 v233, v214, v215
	v_lshlrev_b32_e32 v210, 16, v148
	v_and_b32_e32 v211, 0xffff0000, v148
	v_pk_fma_f32 v[210:211], v[114:115], v[210:211], v[212:213]
	v_cvt_pk_bf16_f32 v234, v210, v211
	v_lshlrev_b32_e32 v214, 16, v149
	v_and_b32_e32 v215, 0xffff0000, v149
	v_pk_fma_f32 v[214:215], v[116:117], v[214:215], v[220:221]
	v_cvt_pk_bf16_f32 v235, v214, v215
	global_store_dwordx4 v197, v[232:235], s[50:51]
	v_lshlrev_b32_e32 v210, 16, v150
	v_and_b32_e32 v211, 0xffff0000, v150
	v_pk_fma_f32 v[210:211], v[86:87], v[210:211], v[212:213]
	v_cvt_pk_bf16_f32 v216, v210, v211
	v_lshlrev_b32_e32 v214, 16, v151
	v_and_b32_e32 v215, 0xffff0000, v151
	v_pk_fma_f32 v[214:215], v[88:89], v[214:215], v[220:221]
	v_cvt_pk_bf16_f32 v217, v214, v215
	v_lshlrev_b32_e32 v210, 16, v152
	v_and_b32_e32 v211, 0xffff0000, v152
	v_pk_fma_f32 v[210:211], v[82:83], v[210:211], v[212:213]
	v_cvt_pk_bf16_f32 v218, v210, v211
	v_lshlrev_b32_e32 v214, 16, v153
	v_and_b32_e32 v215, 0xffff0000, v153
	v_pk_fma_f32 v[214:215], v[84:85], v[214:215], v[220:221]
	v_cvt_pk_bf16_f32 v219, v214, v215
	global_store_dwordx4 v197, v[216:219], s[50:51] offset:256
	v_add_u32_e32 v197, 0x80000, v197
	global_load_dwordx4 v[146:149], v197, s[70:71]
	global_load_dwordx4 v[150:153], v197, s[70:71] offset:256
	s_waitcnt vmcnt(10)
	v_lshlrev_b32_e32 v210, 16, v162
	v_and_b32_e32 v211, 0xffff0000, v162
	v_pk_fma_f32 v[210:211], v[110:111], v[210:211], v[212:213]
	v_cvt_pk_bf16_f32 v232, v210, v211
	v_lshlrev_b32_e32 v214, 16, v163
	v_and_b32_e32 v215, 0xffff0000, v163
	v_pk_fma_f32 v[214:215], v[112:113], v[214:215], v[220:221]
	v_cvt_pk_bf16_f32 v233, v214, v215
	v_lshlrev_b32_e32 v210, 16, v164
	v_and_b32_e32 v211, 0xffff0000, v164
	v_pk_fma_f32 v[210:211], v[106:107], v[210:211], v[212:213]
	v_cvt_pk_bf16_f32 v234, v210, v211
	v_lshlrev_b32_e32 v214, 16, v165
	v_and_b32_e32 v215, 0xffff0000, v165
	v_pk_fma_f32 v[214:215], v[108:109], v[214:215], v[220:221]
	v_cvt_pk_bf16_f32 v235, v214, v215
	global_store_dwordx4 v198, v[232:235], s[50:51]
	v_lshlrev_b32_e32 v210, 16, v166
	v_and_b32_e32 v211, 0xffff0000, v166
	v_pk_fma_f32 v[210:211], v[78:79], v[210:211], v[212:213]
	v_cvt_pk_bf16_f32 v216, v210, v211
	v_lshlrev_b32_e32 v214, 16, v167
	v_and_b32_e32 v215, 0xffff0000, v167
	v_pk_fma_f32 v[214:215], v[80:81], v[214:215], v[220:221]
	v_cvt_pk_bf16_f32 v217, v214, v215
	v_lshlrev_b32_e32 v210, 16, v168
	v_and_b32_e32 v211, 0xffff0000, v168
	v_pk_fma_f32 v[210:211], v[74:75], v[210:211], v[212:213]
	v_cvt_pk_bf16_f32 v218, v210, v211
	v_lshlrev_b32_e32 v214, 16, v169
	v_and_b32_e32 v215, 0xffff0000, v169
	v_pk_fma_f32 v[214:215], v[76:77], v[214:215], v[220:221]
	v_cvt_pk_bf16_f32 v219, v214, v215
	global_store_dwordx4 v198, v[216:219], s[50:51] offset:256
	v_add_u32_e32 v198, 0x80000, v198
	global_load_dwordx4 v[162:165], v198, s[70:71]
	global_load_dwordx4 v[166:169], v198, s[70:71] offset:256
	s_waitcnt vmcnt(12)
; __device__ __forceinline__ u32x4 pack8(f32x4 v0, f32x4 v1) { u32x4 w; w.x = cvt_pk_bf16(v0[0], v0[1]); w.y = cvt_pk_bf16(v0[2], v0[3]); w.z = cvt_pk_bf16(v1[0], v1[1]); w.w = cvt_pk_bf16(v1[2], v1[3]); return w; }
; __device__ __forceinline__ void unpack8(u32x4 w, f32x4& v0, f32x4& v1) { v0 = (f32x4){bflo(w.x), bfhi(w.x), bflo(w.y), bfhi(w.y)}; v1 = (f32x4){bflo(w.z), bfhi(w.z), bflo(w.w), bfhi(w.w)}; }
;     __device__ __forceinline__ void operator()(AccRef acc, const Unit& u, int wr, int wc, int fr, int fq, const float (&pre)[8]) const {
;     ...
;         for (int ai = 0; ai < 2; ++ai) {
;             u32x4 gv[4][2], mv[4][2];
; #pragma unroll
;             for (int m = 0; m < 4; ++m)
; #pragma unroll
;                 for (int bj = 0; bj < 2; ++bj) { const size_t off = (size_t)(row0 + ai * HALF + m * 16) * 2048 + col0 + bj * HALF;
;                     gv[m][bj] = gld16(Gt + off); mv[m][bj] = (u32x4){0u, 0u, 0u, 0u}; if (!first) mv[m][bj] = gld16(Mo + off); }
; #pragma unroll
;             for (int m = 0; m < 4; ++m)
; #pragma unroll
;                 for (int bj = 0; bj < 2; ++bj) { const size_t off = (size_t)(row0 + ai * HALF + m * 16) * 2048 + col0 + bj * HALF;
;                     f32x4 g0, g1; unpack8(gv[m][bj], g0, g1);
;                     f32x4 v0 = g0 * acc[ai][bj][m][0], v1 = g1 * acc[ai][bj][m][1];
;                     { f32x4 p0, p1; unpack8(mv[m][bj], p0, p1); v0 += p0; v1 += p1; }
;                     gst16(Mo + off, pack8(v0, v1)); }
	v_lshlrev_b32_e32 v210, 16, v178
	v_and_b32_e32 v211, 0xffff0000, v178
	v_pk_fma_f32 v[210:211], v[102:103], v[210:211], v[212:213]
	v_cvt_pk_bf16_f32 v232, v210, v211
	v_lshlrev_b32_e32 v214, 16, v179
	v_and_b32_e32 v215, 0xffff0000, v179
	v_pk_fma_f32 v[214:215], v[104:105], v[214:215], v[220:221]
	v_cvt_pk_bf16_f32 v233, v214, v215
	v_lshlrev_b32_e32 v210, 16, v180
	v_and_b32_e32 v211, 0xffff0000, v180
	v_pk_fma_f32 v[210:211], v[98:99], v[210:211], v[212:213]
	v_cvt_pk_bf16_f32 v234, v210, v211
	v_lshlrev_b32_e32 v214, 16, v181
	v_and_b32_e32 v215, 0xffff0000, v181
	v_pk_fma_f32 v[214:215], v[100:101], v[214:215], v[220:221]
	v_cvt_pk_bf16_f32 v235, v214, v215
	global_store_dwordx4 v199, v[232:235], s[50:51]
	v_lshlrev_b32_e32 v210, 16, v182
	v_and_b32_e32 v211, 0xffff0000, v182
	v_pk_fma_f32 v[210:211], v[70:71], v[210:211], v[212:213]
	v_cvt_pk_bf16_f32 v216, v210, v211
	v_lshlrev_b32_e32 v214, 16, v183
	v_and_b32_e32 v215, 0xffff0000, v183
	v_pk_fma_f32 v[214:215], v[72:73], v[214:215], v[220:221]
	v_cvt_pk_bf16_f32 v217, v214, v215
	v_lshlrev_b32_e32 v210, 16, v184
	v_and_b32_e32 v211, 0xffff0000, v184
	v_pk_fma_f32 v[210:211], v[66:67], v[210:211], v[212:213]
	v_cvt_pk_bf16_f32 v218, v210, v211
	v_lshlrev_b32_e32 v214, 16, v185
	v_and_b32_e32 v215, 0xffff0000, v185
	v_pk_fma_f32 v[214:215], v[68:69], v[214:215], v[220:221]
	v_cvt_pk_bf16_f32 v219, v214, v215
	global_store_dwordx4 v199, v[216:219], s[50:51] offset:256
	v_add_u32_e32 v199, 0x80000, v199
	global_load_dwordx4 v[178:181], v199, s[70:71]
	global_load_dwordx4 v[182:185], v199, s[70:71] offset:256
	s_waitcnt vmcnt(12)
	v_lshlrev_b32_e32 v210, 16, v130
	v_and_b32_e32 v211, 0xffff0000, v130
	v_pk_fma_f32 v[210:211], v[62:63], v[210:211], v[212:213]
	v_cvt_pk_bf16_f32 v232, v210, v211
	v_lshlrev_b32_e32 v214, 16, v131
	v_and_b32_e32 v215, 0xffff0000, v131
	v_pk_fma_f32 v[214:215], v[64:65], v[214:215], v[220:221]
	v_cvt_pk_bf16_f32 v233, v214, v215
	v_lshlrev_b32_e32 v210, 16, v132
	v_and_b32_e32 v211, 0xffff0000, v132
	v_pk_fma_f32 v[210:211], v[58:59], v[210:211], v[212:213]
	v_cvt_pk_bf16_f32 v234, v210, v211
	v_lshlrev_b32_e32 v214, 16, v133
	v_and_b32_e32 v215, 0xffff0000, v133
	v_pk_fma_f32 v[214:215], v[60:61], v[214:215], v[220:221]
	v_cvt_pk_bf16_f32 v235, v214, v215
	global_store_dwordx4 v196, v[232:235], s[50:51]
	v_lshlrev_b32_e32 v210, 16, v134
	v_and_b32_e32 v211, 0xffff0000, v134
	v_pk_fma_f32 v[210:211], v[30:31], v[210:211], v[212:213]
	v_cvt_pk_bf16_f32 v216, v210, v211
	v_lshlrev_b32_e32 v214, 16, v135
	v_and_b32_e32 v215, 0xffff0000, v135
	v_pk_fma_f32 v[214:215], v[32:33], v[214:215], v[220:221]
	v_cvt_pk_bf16_f32 v217, v214, v215
	v_lshlrev_b32_e32 v210, 16, v136
	v_and_b32_e32 v211, 0xffff0000, v136
	v_pk_fma_f32 v[210:211], v[26:27], v[210:211], v[212:213]
	v_cvt_pk_bf16_f32 v218, v210, v211
	v_lshlrev_b32_e32 v214, 16, v137
	v_and_b32_e32 v215, 0xffff0000, v137
	v_pk_fma_f32 v[214:215], v[28:29], v[214:215], v[220:221]
	v_cvt_pk_bf16_f32 v219, v214, v215
	global_store_dwordx4 v196, v[216:219], s[50:51] offset:256
	s_waitcnt vmcnt(10)
	v_lshlrev_b32_e32 v210, 16, v146
	v_and_b32_e32 v211, 0xffff0000, v146
	v_pk_fma_f32 v[210:211], v[54:55], v[210:211], v[212:213]
	v_cvt_pk_bf16_f32 v232, v210, v211
	v_lshlrev_b32_e32 v214, 16, v147
	v_and_b32_e32 v215, 0xffff0000, v147
	v_pk_fma_f32 v[214:215], v[56:57], v[214:215], v[220:221]
	v_cvt_pk_bf16_f32 v233, v214, v215
	v_lshlrev_b32_e32 v210, 16, v148
	v_and_b32_e32 v211, 0xffff0000, v148
	v_pk_fma_f32 v[210:211], v[50:51], v[210:211], v[212:213]
	v_cvt_pk_bf16_f32 v234, v210, v211
	v_lshlrev_b32_e32 v214, 16, v149
	v_and_b32_e32 v215, 0xffff0000, v149
	v_pk_fma_f32 v[214:215], v[52:53], v[214:215], v[220:221]
	v_cvt_pk_bf16_f32 v235, v214, v215
	global_store_dwordx4 v197, v[232:235], s[50:51]
	v_lshlrev_b32_e32 v210, 16, v150
	v_and_b32_e32 v211, 0xffff0000, v150
	v_pk_fma_f32 v[210:211], v[22:23], v[210:211], v[212:213]
	v_cvt_pk_bf16_f32 v216, v210, v211
	v_lshlrev_b32_e32 v214, 16, v151
	v_and_b32_e32 v215, 0xffff0000, v151
	v_pk_fma_f32 v[214:215], v[24:25], v[214:215], v[220:221]
	v_cvt_pk_bf16_f32 v217, v214, v215
	v_lshlrev_b32_e32 v210, 16, v152
	v_and_b32_e32 v211, 0xffff0000, v152
	v_pk_fma_f32 v[210:211], v[18:19], v[210:211], v[212:213]
	v_cvt_pk_bf16_f32 v218, v210, v211
	v_lshlrev_b32_e32 v214, 16, v153
	v_and_b32_e32 v215, 0xffff0000, v153
	v_pk_fma_f32 v[214:215], v[20:21], v[214:215], v[220:221]
	v_cvt_pk_bf16_f32 v219, v214, v215
	global_store_dwordx4 v197, v[216:219], s[50:51] offset:256
	s_waitcnt vmcnt(8)
	v_lshlrev_b32_e32 v210, 16, v162
	v_and_b32_e32 v211, 0xffff0000, v162
	v_pk_fma_f32 v[210:211], v[46:47], v[210:211], v[212:213]
	v_cvt_pk_bf16_f32 v232, v210, v211
	v_lshlrev_b32_e32 v214, 16, v163
	v_and_b32_e32 v215, 0xffff0000, v163
	v_pk_fma_f32 v[214:215], v[48:49], v[214:215], v[220:221]
	v_cvt_pk_bf16_f32 v233, v214, v215
	v_lshlrev_b32_e32 v210, 16, v164
	v_and_b32_e32 v211, 0xffff0000, v164
	v_pk_fma_f32 v[210:211], v[42:43], v[210:211], v[212:213]
	v_cvt_pk_bf16_f32 v234, v210, v211
	v_lshlrev_b32_e32 v214, 16, v165
	v_and_b32_e32 v215, 0xffff0000, v165
	v_pk_fma_f32 v[214:215], v[44:45], v[214:215], v[220:221]
	v_cvt_pk_bf16_f32 v235, v214, v215
	global_store_dwordx4 v198, v[232:235], s[50:51]
	v_lshlrev_b32_e32 v210, 16, v166
	v_and_b32_e32 v211, 0xffff0000, v166
	v_pk_fma_f32 v[210:211], v[14:15], v[210:211], v[212:213]
	v_cvt_pk_bf16_f32 v216, v210, v211
	v_lshlrev_b32_e32 v214, 16, v167
	v_and_b32_e32 v215, 0xffff0000, v167
	v_pk_fma_f32 v[214:215], v[16:17], v[214:215], v[220:221]
	v_cvt_pk_bf16_f32 v217, v214, v215
	v_lshlrev_b32_e32 v210, 16, v168
	v_and_b32_e32 v211, 0xffff0000, v168
	v_pk_fma_f32 v[210:211], v[10:11], v[210:211], v[212:213]
	v_cvt_pk_bf16_f32 v218, v210, v211
	v_lshlrev_b32_e32 v214, 16, v169
	v_and_b32_e32 v215, 0xffff0000, v169
	v_pk_fma_f32 v[214:215], v[12:13], v[214:215], v[220:221]
	v_cvt_pk_bf16_f32 v219, v214, v215
	global_store_dwordx4 v198, v[216:219], s[50:51] offset:256
	s_waitcnt vmcnt(6)
; __device__ __forceinline__ u32x4 pack8(f32x4 v0, f32x4 v1) { u32x4 w; w.x = cvt_pk_bf16(v0[0], v0[1]); w.y = cvt_pk_bf16(v0[2], v0[3]); w.z = cvt_pk_bf16(v1[0], v1[1]); w.w = cvt_pk_bf16(v1[2], v1[3]); return w; }
; __device__ __forceinline__ void unpack8(u32x4 w, f32x4& v0, f32x4& v1) { v0 = (f32x4){bflo(w.x), bfhi(w.x), bflo(w.y), bfhi(w.y)}; v1 = (f32x4){bflo(w.z), bfhi(w.z), bflo(w.w), bfhi(w.w)}; }
; template <class Epi, bool DYN = false>
; __device__ __forceinline__ void gemm_phase(LAS unsigned char* lds, const Gemm g, const Epi& E, int wave, unsigned* ctr = nullptr) {
;     ...
;         if (!has_next) break;
; #pragma unroll
;         for (int a = 0; a < 2; ++a)
; #pragma unroll
;             for (int b = 0; b < 2; ++b)
; #pragma unroll
;                 for (int m = 0; m < 4; ++m)
; #pragma unroll
;                     for (int n = 0; n < 2; ++n) acc[a][b][m][n] = (f32x4){0.f, 0.f, 0.f, 0.f};
;         cur = nxt; cA = nA; cB = nB; ++ui;
;     __device__ __forceinline__ void operator()(AccRef acc, const Unit& u, int wr, int wc, int fr, int fq, const float (&pre)[8]) const {
;     ...
;                 for (int bj = 0; bj < 2; ++bj) { const size_t off = (size_t)(row0 + ai * HALF + m * 16) * 2048 + col0 + bj * HALF;
;                     f32x4 g0, g1; unpack8(gv[m][bj], g0, g1);
;                     f32x4 v0 = g0 * acc[ai][bj][m][0], v1 = g1 * acc[ai][bj][m][1];
;                     { f32x4 p0, p1; unpack8(mv[m][bj], p0, p1); v0 += p0; v1 += p1; }
;                     gst16(Mo + off, pack8(v0, v1)); }
	v_lshlrev_b32_e32 v210, 16, v178
	v_and_b32_e32 v211, 0xffff0000, v178
	v_pk_fma_f32 v[210:211], v[38:39], v[210:211], v[212:213]
	v_cvt_pk_bf16_f32 v232, v210, v211
	v_lshlrev_b32_e32 v214, 16, v179
	v_and_b32_e32 v215, 0xffff0000, v179
	v_pk_fma_f32 v[214:215], v[40:41], v[214:215], v[220:221]
	v_cvt_pk_bf16_f32 v233, v214, v215
	v_lshlrev_b32_e32 v210, 16, v180
	v_and_b32_e32 v211, 0xffff0000, v180
	v_pk_fma_f32 v[210:211], v[34:35], v[210:211], v[212:213]
	v_cvt_pk_bf16_f32 v234, v210, v211
	v_lshlrev_b32_e32 v214, 16, v181
	v_and_b32_e32 v215, 0xffff0000, v181
	v_pk_fma_f32 v[214:215], v[36:37], v[214:215], v[220:221]
	v_cvt_pk_bf16_f32 v235, v214, v215
	global_store_dwordx4 v199, v[232:235], s[50:51]
	v_lshlrev_b32_e32 v210, 16, v182
	v_and_b32_e32 v211, 0xffff0000, v182
	v_pk_fma_f32 v[210:211], v[6:7], v[210:211], v[212:213]
	v_cvt_pk_bf16_f32 v216, v210, v211
	v_lshlrev_b32_e32 v214, 16, v183
	v_and_b32_e32 v215, 0xffff0000, v183
	v_pk_fma_f32 v[214:215], v[8:9], v[214:215], v[220:221]
	v_cvt_pk_bf16_f32 v217, v214, v215
	v_lshlrev_b32_e32 v210, 16, v184
	v_and_b32_e32 v211, 0xffff0000, v184
	v_pk_fma_f32 v[210:211], v[2:3], v[210:211], v[212:213]
	v_cvt_pk_bf16_f32 v218, v210, v211
	v_lshlrev_b32_e32 v214, 16, v185
	v_and_b32_e32 v215, 0xffff0000, v185
	v_pk_fma_f32 v[214:215], v[4:5], v[214:215], v[220:221]
	v_cvt_pk_bf16_f32 v219, v214, v215
	global_store_dwordx4 v199, v[216:219], s[50:51] offset:256
.Lmrg_done:
	s_andn2_b64 vcc, exec, s[38:39]
	s_cbranch_vccnz .LBB0_114
	v_mov_b32_e32 v2, 0
	s_mov_b32 s60, s62
	s_mov_b32 s58, s72
	s_mov_b64 s[66:67], s[76:77]
	s_mov_b64 s[68:69], s[74:75]
	s_mov_b32 s87, s95
	v_mov_b32_e32 v3, v2
	v_mov_b32_e32 v4, v2
	v_mov_b32_e32 v5, v2
	v_mov_b32_e32 v6, v2
	v_mov_b32_e32 v7, v2
	v_mov_b32_e32 v8, v2
	v_mov_b32_e32 v9, v2
	v_mov_b32_e32 v10, v2
	v_mov_b32_e32 v11, v2
	v_mov_b32_e32 v12, v2
	v_mov_b32_e32 v13, v2
	v_mov_b32_e32 v14, v2
	v_mov_b32_e32 v15, v2
	v_mov_b32_e32 v16, v2
	v_mov_b32_e32 v17, v2
	v_mov_b32_e32 v18, v2
	v_mov_b32_e32 v19, v2
	v_mov_b32_e32 v20, v2
	v_mov_b32_e32 v21, v2
	v_mov_b32_e32 v22, v2
	v_mov_b32_e32 v23, v2
	v_mov_b32_e32 v24, v2
	v_mov_b32_e32 v25, v2
	v_mov_b32_e32 v26, v2
	v_mov_b32_e32 v27, v2
	v_mov_b32_e32 v28, v2
	v_mov_b32_e32 v29, v2
	v_mov_b32_e32 v30, v2
	v_mov_b32_e32 v31, v2
	v_mov_b32_e32 v32, v2
	v_mov_b32_e32 v33, v2
	v_mov_b32_e32 v34, v2
	v_mov_b32_e32 v35, v2
	v_mov_b32_e32 v36, v2
	v_mov_b32_e32 v37, v2
	v_mov_b32_e32 v38, v2
	v_mov_b32_e32 v39, v2
	v_mov_b32_e32 v40, v2
	v_mov_b32_e32 v41, v2
	v_mov_b32_e32 v42, v2
	v_mov_b32_e32 v43, v2
	v_mov_b32_e32 v44, v2
	v_mov_b32_e32 v45, v2
	v_mov_b32_e32 v46, v2
	v_mov_b32_e32 v47, v2
	v_mov_b32_e32 v48, v2
	v_mov_b32_e32 v49, v2
	v_mov_b32_e32 v50, v2
	v_mov_b32_e32 v51, v2
	v_mov_b32_e32 v52, v2
	v_mov_b32_e32 v53, v2
	v_mov_b32_e32 v54, v2
	v_mov_b32_e32 v55, v2
	v_mov_b32_e32 v56, v2
	v_mov_b32_e32 v57, v2
	v_mov_b32_e32 v58, v2
	v_mov_b32_e32 v59, v2
	v_mov_b32_e32 v60, v2
	v_mov_b32_e32 v61, v2
	v_mov_b32_e32 v62, v2
	v_mov_b32_e32 v63, v2
	v_mov_b32_e32 v64, v2
	v_mov_b32_e32 v65, v2
	v_mov_b32_e32 v66, v2
	v_mov_b32_e32 v67, v2
	v_mov_b32_e32 v68, v2
	v_mov_b32_e32 v69, v2
	v_mov_b32_e32 v70, v2
	v_mov_b32_e32 v71, v2
	v_mov_b32_e32 v72, v2
	v_mov_b32_e32 v73, v2
	v_mov_b32_e32 v74, v2
	v_mov_b32_e32 v75, v2
	v_mov_b32_e32 v76, v2
	v_mov_b32_e32 v77, v2
	v_mov_b32_e32 v78, v2
	v_mov_b32_e32 v79, v2
	v_mov_b32_e32 v80, v2
	v_mov_b32_e32 v81, v2
	v_mov_b32_e32 v82, v2
	v_mov_b32_e32 v83, v2
	v_mov_b32_e32 v84, v2
	v_mov_b32_e32 v85, v2
	v_mov_b32_e32 v86, v2
	v_mov_b32_e32 v87, v2
	v_mov_b32_e32 v88, v2
	v_mov_b32_e32 v89, v2
	v_mov_b32_e32 v90, v2
	v_mov_b32_e32 v91, v2
	v_mov_b32_e32 v92, v2
	v_mov_b32_e32 v93, v2
	v_mov_b32_e32 v94, v2
	v_mov_b32_e32 v95, v2
	v_mov_b32_e32 v96, v2
	v_mov_b32_e32 v97, v2
	v_mov_b32_e32 v98, v2
	v_mov_b32_e32 v99, v2
	v_mov_b32_e32 v100, v2
	v_mov_b32_e32 v101, v2
	v_mov_b32_e32 v102, v2
	v_mov_b32_e32 v103, v2
	v_mov_b32_e32 v104, v2
	v_mov_b32_e32 v105, v2
	v_mov_b32_e32 v106, v2
	v_mov_b32_e32 v107, v2
	v_mov_b32_e32 v108, v2
	v_mov_b32_e32 v109, v2
	v_mov_b32_e32 v110, v2
	v_mov_b32_e32 v111, v2
	v_mov_b32_e32 v112, v2
	v_mov_b32_e32 v113, v2
	v_mov_b32_e32 v114, v2
	v_mov_b32_e32 v115, v2
	v_mov_b32_e32 v116, v2
	v_mov_b32_e32 v117, v2
	v_mov_b32_e32 v118, v2
	v_mov_b32_e32 v119, v2
	v_mov_b32_e32 v120, v2
	v_mov_b32_e32 v121, v2
	v_mov_b32_e32 v122, v2
	v_mov_b32_e32 v123, v2
	v_mov_b32_e32 v124, v2
	v_mov_b32_e32 v125, v2
	v_mov_b32_e32 v126, v2
	v_mov_b32_e32 v127, v2
	v_mov_b32_e32 v128, v2
	v_mov_b32_e32 v129, v2
	s_branch .LBB0_114
